# scan: one-hot matrix and lane offsets built once per item, DPP gap fillers rebalanced (fewer s_nop)
# speedup vs baseline: 1.0148x; 1.0053x over previous
; #define YRED4(dst) { \
;           float a0 = b3 ? p2 : p0, a1 = b3 ? p3 : p1; const float s0 = b3 ? p0 : p2, s1 = b3 ? p1 : p3; \
;           a0 += dppf<0x128>(s0); a1 += dppf<0x128>(s1); \
;           float cc = b2 ? a1 : a0; const float dd = b2 ? a0 : a1; \
;           cc += dppf<0x141>(dd); cc += dppf<0xB1>(cc); cc += dppf<0x4E>(cc); dst = cc; }
; __device__ __forceinline__ void phase_scan(KP p) {
;     ...
;       } else if (c >= 0) {
;         const int buf = c & 1;
;         const float* fbase = feat + (buf * 32) * 320 + cs * 4;
;         const float* vb4 = vbuf + (buf * 16 + rowl) * 32;
;         const bool b3 = (cs & 8) != 0, b2 = (cs & 4) != 0;
;         float* yb = ybuf + (buf * 32 + (b3 ? 2 : 0) + (b2 ? 1 : 0)) * 16 + rowl;
;         float4 Ar, Aw, Ak, An, Ab, Br, Bw, Bk, Bn, Bb, Cr, Cw, Ck, Cn, Cb, Dr, Dw, Dk, Dn, Db;
;         float4 vcur = *(const float4*)vb4, vnext;
;         float q0 = 0.f, q1 = 0.f, q2 = 0.f, q3 = 0.f, p0 = 0.f, p1 = 0.f, p2 = 0.f, p3 = 0.f;
;     ...
;         SLD(A, 0); SLD(B, 1);
;         for (int g = 0; g < 8; ++g) {
;           const int st = g * 4;
;           SLD(C, st + 2); vnext = *(const float4*)(vb4 + st + 4);
;           __builtin_amdgcn_sched_barrier(0);
;           if (g > 0) { float yv; YRED4(yv); yb[(st - 4) * 16] = yv; }
;           SCOMP(A, vcur.x, q0);
;           SLD(D, st + 3);
;           __builtin_amdgcn_sched_barrier(0);
;           SCOMP(B, vcur.y, q1);
;           SLD(A, st + 4);
;           __builtin_amdgcn_sched_barrier(0);
;           SCOMP(C, vcur.z, q2);
;           SLD(B, st + 5);
;           __builtin_amdgcn_sched_barrier(0);
;           SCOMP(D, vcur.w, q3);
;           vcur = vnext; p0 = q0; p1 = q1; p2 = q2; p3 = q3;
;         }
;         { float yv; YRED4(yv); yb[28 * 16] = yv; }
.LBB0_770:
	s_or_saveexec_b64 s[50:51], s[70:71]
	s_movk_i32 s71, 0x600
	s_xor_b64 exec, exec, s[50:51]
	s_cbranch_execz .LBB0_755
	s_cmp_lt_i32 s18, 0
	s_cbranch_scc1 .LBB0_755
	s_and_b32 s70, s18, 1
	s_cmp_lg_u32 s18, 0
	s_cbranch_scc1 .Lscan_hot
	v_and_b32_e32 v93, 63, v135
	v_bfe_u32 v94, v93, 3, 2
	v_and_b32_e32 v95, 3, v93
	v_lshl_add_u32 v94, v94, 2, v95
	v_lshrrev_b32_e32 v95, 5, v93
	v_lshl_add_u32 v94, v94, 1, v95
	s_mov_b32 s19, 0x16000
	v_lshl_add_u32 v129, v94, 4, s19
	v_and_b32_e32 v94, 15, v93
	v_lshlrev_b32_e32 v95, 3, v95
	v_sub_u32_e32 v94, v94, v95
	v_and_b32_e32 v95, 1, v94
	v_lshlrev_b32_e32 v95, 4, v95
	v_mov_b32_e32 v93, 0x3f80
	v_lshlrev_b32_e32 v93, v95, v93
	v_lshrrev_b32_e32 v94, 1, v94
	v_cmp_eq_u32_e64 s[74:75], 0, v94
	s_nop 1
	v_cndmask_b32_e64 v124, 0, v93, s[74:75]
	v_cmp_eq_u32_e64 s[74:75], 1, v94
	s_nop 1
	v_cndmask_b32_e64 v125, 0, v93, s[74:75]
	v_cmp_eq_u32_e64 s[74:75], 2, v94
	s_nop 1
	v_cndmask_b32_e64 v126, 0, v93, s[74:75]
	v_cmp_eq_u32_e64 s[74:75], 3, v94
	s_nop 1
	v_cndmask_b32_e64 v127, 0, v93, s[74:75]
.Lscan_hot:
	s_mul_i32 s19, s70, 0x4400
	v_add_u32_e32 v128, s19, v129
	ds_read_b128 v[108:111], v128
	ds_read_b128 v[112:115], v128 offset:544
	s_mul_i32 s19, s70, 0xa000
	v_lshl_add_u32 v106, s70, 11, v121
	v_add_u32_e32 v105, s19, v120
	v_lshl_add_u32 v107, s70, 11, v146
	ds_read_b128 v[80:83], v106
	ds_read_b128 v[16:19], v105 offset:256
	ds_read_b128 v[36:39], v105 offset:1536
	s_waitcnt lgkmcnt(4)
	v_mfma_f32_32x32x16_bf16 v[0:15], v[108:111], v[124:127], 0
	s_waitcnt lgkmcnt(3)
	v_mfma_f32_32x32x16_bf16 v[20:35], v[112:115], v[124:127], 0
	ds_read_b128 v[108:111], v128 offset:1088
	s_nop 7
	s_nop 3
	s_waitcnt lgkmcnt(2)
	v_pk_mul_f32 v[84:85], v[116:117], v[8:9]
	v_pk_mul_f32 v[86:87], v[80:81], v[4:5] op_sel_hi:[0,1]
	v_pk_fma_f32 v[84:85], v[118:119], v[10:11], v[84:85]
	v_pk_mul_f32 v[88:89], v[80:81], v[6:7] op_sel_hi:[0,1]
	v_add_f32_e32 v92, v84, v85
	v_pk_fma_f32 v[86:87], v[116:117], v[16:17], v[86:87]
	ds_read_b128 v[112:115], v128 offset:1632
	v_add_f32_dpp v92, v92, v92 quad_perm:[1,0,3,2] row_mask:0xf bank_mask:0xf bound_ctrl:1
	v_pk_fma_f32 v[88:89], v[118:119], v[18:19], v[88:89]
	s_waitcnt lgkmcnt(1)
	v_mfma_f32_32x32x16_bf16 v[40:55], v[108:111], v[124:127], 0
	v_add_f32_dpp v92, v92, v92 quad_perm:[2,3,0,1] row_mask:0xf bank_mask:0xf bound_ctrl:1
	s_nop 1
	v_add_f32_dpp v92, v92, v92 row_half_mirror row_mask:0xf bank_mask:0xf bound_ctrl:1
	ds_read_b128 v[56:59], v105 offset:2816
	s_nop 0
	v_add_f32_dpp v92, v92, v92 row_mirror row_mask:0xf bank_mask:0xf bound_ctrl:1
	v_pk_fma_f32 v[116:117], v[12:13], v[92:93], v[86:87] op_sel_hi:[1,0,1]
	v_pk_fma_f32 v[118:119], v[14:15], v[92:93], v[88:89] op_sel_hi:[1,0,1]
	v_pk_mul_f32 v[84:85], v[116:117], v[28:29]
	v_pk_mul_f32 v[86:87], v[80:81], v[24:25] op_sel:[1,0]
	v_pk_fma_f32 v[84:85], v[118:119], v[30:31], v[84:85]
	v_pk_mul_f32 v[88:89], v[80:81], v[26:27] op_sel:[1,0]
	v_add_f32_e32 v92, v84, v85
	v_pk_fma_f32 v[86:87], v[116:117], v[36:37], v[86:87]
	v_pk_mul_f32 v[90:91], v[116:117], v[0:1]
	v_add_f32_dpp v92, v92, v92 quad_perm:[1,0,3,2] row_mask:0xf bank_mask:0xf bound_ctrl:1
	v_pk_fma_f32 v[88:89], v[118:119], v[38:39], v[88:89]
	v_pk_fma_f32 v[90:91], v[118:119], v[2:3], v[90:91]
	s_waitcnt lgkmcnt(1)
	v_mfma_f32_32x32x16_bf16 v[60:75], v[112:115], v[124:127], 0
	v_add_f32_dpp v92, v92, v92 quad_perm:[2,3,0,1] row_mask:0xf bank_mask:0xf bound_ctrl:1
	v_add_f32_e32 v96, v90, v91
	ds_read_b128 v[108:111], v128 offset:2176
	v_add_f32_dpp v92, v92, v92 row_half_mirror row_mask:0xf bank_mask:0xf bound_ctrl:1
	ds_read_b128 v[76:79], v105 offset:4096
	s_nop 0
	v_add_f32_dpp v92, v92, v92 row_mirror row_mask:0xf bank_mask:0xf bound_ctrl:1
	v_pk_fma_f32 v[116:117], v[32:33], v[92:93], v[86:87] op_sel_hi:[1,0,1]
	v_pk_fma_f32 v[118:119], v[34:35], v[92:93], v[88:89] op_sel_hi:[1,0,1]
	s_waitcnt lgkmcnt(2)
	v_pk_mul_f32 v[84:85], v[116:117], v[48:49]
	v_pk_mul_f32 v[86:87], v[82:83], v[44:45] op_sel_hi:[0,1]
	v_pk_fma_f32 v[84:85], v[118:119], v[50:51], v[84:85]
	v_pk_mul_f32 v[88:89], v[82:83], v[46:47] op_sel_hi:[0,1]
	v_add_f32_e32 v92, v84, v85
	v_pk_fma_f32 v[86:87], v[116:117], v[56:57], v[86:87]
	v_pk_mul_f32 v[90:91], v[116:117], v[20:21]
	v_add_f32_dpp v92, v92, v92 quad_perm:[1,0,3,2] row_mask:0xf bank_mask:0xf bound_ctrl:1
	v_pk_fma_f32 v[88:89], v[118:119], v[58:59], v[88:89]
	v_pk_fma_f32 v[90:91], v[118:119], v[22:23], v[90:91]
	s_waitcnt lgkmcnt(1)
	v_mfma_f32_32x32x16_bf16 v[0:15], v[108:111], v[124:127], 0
	v_add_f32_dpp v92, v92, v92 quad_perm:[2,3,0,1] row_mask:0xf bank_mask:0xf bound_ctrl:1
	v_add_f32_e32 v97, v90, v91
	ds_read_b128 v[112:115], v128 offset:2720
	v_add_f32_dpp v92, v92, v92 row_half_mirror row_mask:0xf bank_mask:0xf bound_ctrl:1
	ds_read_b128 v[16:19], v105 offset:5376
	s_nop 0
	v_add_f32_dpp v92, v92, v92 row_mirror row_mask:0xf bank_mask:0xf bound_ctrl:1
	v_pk_fma_f32 v[116:117], v[52:53], v[92:93], v[86:87] op_sel_hi:[1,0,1]
	v_pk_fma_f32 v[118:119], v[54:55], v[92:93], v[88:89] op_sel_hi:[1,0,1]
	s_waitcnt lgkmcnt(2)
	v_pk_mul_f32 v[84:85], v[116:117], v[68:69]
	v_pk_mul_f32 v[86:87], v[82:83], v[64:65] op_sel:[1,0]
	v_pk_fma_f32 v[84:85], v[118:119], v[70:71], v[84:85]
	v_pk_mul_f32 v[88:89], v[82:83], v[66:67] op_sel:[1,0]
	ds_read_b128 v[80:83], v106 offset:16
	v_add_f32_e32 v92, v84, v85
	v_pk_fma_f32 v[86:87], v[116:117], v[76:77], v[86:87]
	v_pk_mul_f32 v[90:91], v[116:117], v[40:41]
	v_add_f32_dpp v92, v92, v92 quad_perm:[1,0,3,2] row_mask:0xf bank_mask:0xf bound_ctrl:1
	v_pk_fma_f32 v[88:89], v[118:119], v[78:79], v[88:89]
	v_pk_fma_f32 v[90:91], v[118:119], v[42:43], v[90:91]
	s_waitcnt lgkmcnt(2)
; #define YRED4(dst) { \
;           float a0 = b3 ? p2 : p0, a1 = b3 ? p3 : p1; const float s0 = b3 ? p0 : p2, s1 = b3 ? p1 : p3; \
;           a0 += dppf<0x128>(s0); a1 += dppf<0x128>(s1); \
;           float cc = b2 ? a1 : a0; const float dd = b2 ? a0 : a1; \
;           cc += dppf<0x141>(dd); cc += dppf<0xB1>(cc); cc += dppf<0x4E>(cc); dst = cc; }
; __device__ __forceinline__ void phase_scan(KP p) {
;     ...
;         SLD(A, 0); SLD(B, 1);
;         for (int g = 0; g < 8; ++g) {
;           const int st = g * 4;
;           SLD(C, st + 2); vnext = *(const float4*)(vb4 + st + 4);
;           __builtin_amdgcn_sched_barrier(0);
;           if (g > 0) { float yv; YRED4(yv); yb[(st - 4) * 16] = yv; }
;           SCOMP(A, vcur.x, q0);
;           SLD(D, st + 3);
;           __builtin_amdgcn_sched_barrier(0);
;           SCOMP(B, vcur.y, q1);
;           SLD(A, st + 4);
;           __builtin_amdgcn_sched_barrier(0);
;           SCOMP(C, vcur.z, q2);
;           SLD(B, st + 5);
;           __builtin_amdgcn_sched_barrier(0);
;           SCOMP(D, vcur.w, q3);
;           vcur = vnext; p0 = q0; p1 = q1; p2 = q2; p3 = q3;
;         }
	v_mfma_f32_32x32x16_bf16 v[20:35], v[112:115], v[124:127], 0
	v_add_f32_dpp v92, v92, v92 quad_perm:[2,3,0,1] row_mask:0xf bank_mask:0xf bound_ctrl:1
	v_add_f32_e32 v98, v90, v91
	ds_read_b128 v[108:111], v128 offset:3264
	v_add_f32_dpp v92, v92, v92 row_half_mirror row_mask:0xf bank_mask:0xf bound_ctrl:1
	ds_read_b128 v[36:39], v105 offset:6656
	s_nop 0
	v_add_f32_dpp v92, v92, v92 row_mirror row_mask:0xf bank_mask:0xf bound_ctrl:1
	v_pk_fma_f32 v[116:117], v[72:73], v[92:93], v[86:87] op_sel_hi:[1,0,1]
	v_pk_fma_f32 v[118:119], v[74:75], v[92:93], v[88:89] op_sel_hi:[1,0,1]
	s_waitcnt lgkmcnt(2)
	v_pk_mul_f32 v[84:85], v[116:117], v[8:9]
	v_pk_mul_f32 v[86:87], v[80:81], v[4:5] op_sel_hi:[0,1]
	v_pk_fma_f32 v[84:85], v[118:119], v[10:11], v[84:85]
	v_pk_mul_f32 v[88:89], v[80:81], v[6:7] op_sel_hi:[0,1]
	v_add_f32_e32 v92, v84, v85
	v_pk_fma_f32 v[86:87], v[116:117], v[16:17], v[86:87]
	v_pk_mul_f32 v[90:91], v[116:117], v[60:61]
	v_add_f32_dpp v92, v92, v92 quad_perm:[1,0,3,2] row_mask:0xf bank_mask:0xf bound_ctrl:1
	v_pk_fma_f32 v[88:89], v[118:119], v[18:19], v[88:89]
	v_pk_fma_f32 v[90:91], v[118:119], v[62:63], v[90:91]
	s_waitcnt lgkmcnt(1)
	v_mfma_f32_32x32x16_bf16 v[40:55], v[108:111], v[124:127], 0
	v_add_f32_dpp v92, v92, v92 quad_perm:[2,3,0,1] row_mask:0xf bank_mask:0xf bound_ctrl:1
	v_add_f32_e32 v99, v90, v91
	ds_read_b128 v[112:115], v128 offset:3808
	v_cndmask_b32_e64 v100, v98, v96, s[38:39]
	v_cndmask_b32_e64 v102, v96, v98, s[38:39]
	v_add_f32_dpp v92, v92, v92 row_half_mirror row_mask:0xf bank_mask:0xf bound_ctrl:1
	ds_read_b128 v[56:59], v105 offset:7936
	v_cndmask_b32_e64 v101, v99, v97, s[38:39]
	v_cndmask_b32_e64 v103, v97, v99, s[38:39]
	v_add_f32_dpp v92, v92, v92 row_mirror row_mask:0xf bank_mask:0xf bound_ctrl:1
	v_pk_fma_f32 v[116:117], v[12:13], v[92:93], v[86:87] op_sel_hi:[1,0,1]
	v_pk_fma_f32 v[118:119], v[14:15], v[92:93], v[88:89] op_sel_hi:[1,0,1]
	s_waitcnt lgkmcnt(2)
	v_pk_mul_f32 v[84:85], v[116:117], v[28:29]
	v_pk_mul_f32 v[86:87], v[80:81], v[24:25] op_sel:[1,0]
	v_pk_fma_f32 v[84:85], v[118:119], v[30:31], v[84:85]
	v_pk_mul_f32 v[88:89], v[80:81], v[26:27] op_sel:[1,0]
	v_add_f32_e32 v92, v84, v85
	v_pk_fma_f32 v[86:87], v[116:117], v[36:37], v[86:87]
	v_pk_mul_f32 v[90:91], v[116:117], v[0:1]
	v_add_f32_dpp v92, v92, v92 quad_perm:[1,0,3,2] row_mask:0xf bank_mask:0xf bound_ctrl:1
	v_pk_fma_f32 v[88:89], v[118:119], v[38:39], v[88:89]
	v_pk_fma_f32 v[90:91], v[118:119], v[2:3], v[90:91]
	s_waitcnt lgkmcnt(1)
	v_mfma_f32_32x32x16_bf16 v[60:75], v[112:115], v[124:127], 0
	v_add_f32_dpp v92, v92, v92 quad_perm:[2,3,0,1] row_mask:0xf bank_mask:0xf bound_ctrl:1
	v_add_f32_e32 v96, v90, v91
	ds_read_b128 v[108:111], v128 offset:4352
	v_add_f32_dpp v102, v102, v100 row_ror:8 row_mask:0xf bank_mask:0xf bound_ctrl:1
	v_add_f32_dpp v92, v92, v92 row_half_mirror row_mask:0xf bank_mask:0xf bound_ctrl:1
	ds_read_b128 v[76:79], v105 offset:9216
	v_add_f32_dpp v103, v103, v101 row_ror:8 row_mask:0xf bank_mask:0xf bound_ctrl:1
	v_add_f32_dpp v92, v92, v92 row_mirror row_mask:0xf bank_mask:0xf bound_ctrl:1
	v_cndmask_b32_e64 v104, v103, v102, s[40:41]
	v_cndmask_b32_e64 v102, v102, v103, s[40:41]
	v_pk_fma_f32 v[116:117], v[32:33], v[92:93], v[86:87] op_sel_hi:[1,0,1]
	v_pk_fma_f32 v[118:119], v[34:35], v[92:93], v[88:89] op_sel_hi:[1,0,1]
	s_waitcnt lgkmcnt(2)
	v_pk_mul_f32 v[84:85], v[116:117], v[48:49]
	v_pk_mul_f32 v[86:87], v[82:83], v[44:45] op_sel_hi:[0,1]
	v_pk_fma_f32 v[84:85], v[118:119], v[50:51], v[84:85]
	v_pk_mul_f32 v[88:89], v[82:83], v[46:47] op_sel_hi:[0,1]
	v_add_f32_e32 v92, v84, v85
	v_pk_fma_f32 v[86:87], v[116:117], v[56:57], v[86:87]
	v_pk_mul_f32 v[90:91], v[116:117], v[20:21]
	v_add_f32_dpp v92, v92, v92 quad_perm:[1,0,3,2] row_mask:0xf bank_mask:0xf bound_ctrl:1
	v_pk_fma_f32 v[88:89], v[118:119], v[58:59], v[88:89]
	v_pk_fma_f32 v[90:91], v[118:119], v[22:23], v[90:91]
	s_waitcnt lgkmcnt(1)
	v_mfma_f32_32x32x16_bf16 v[0:15], v[108:111], v[124:127], 0
	v_add_f32_dpp v92, v92, v92 quad_perm:[2,3,0,1] row_mask:0xf bank_mask:0xf bound_ctrl:1
	v_add_f32_e32 v97, v90, v91
	ds_read_b128 v[112:115], v128 offset:4896
	v_add_f32_dpp v92, v92, v92 row_half_mirror row_mask:0xf bank_mask:0xf bound_ctrl:1
	ds_read_b128 v[16:19], v105 offset:10496
	v_add_f32_dpp v102, v102, v104 row_half_mirror row_mask:0xf bank_mask:0xf bound_ctrl:1
	v_add_f32_dpp v92, v92, v92 row_mirror row_mask:0xf bank_mask:0xf bound_ctrl:1
	v_pk_fma_f32 v[116:117], v[52:53], v[92:93], v[86:87] op_sel_hi:[1,0,1]
	v_pk_fma_f32 v[118:119], v[54:55], v[92:93], v[88:89] op_sel_hi:[1,0,1]
	v_add_f32_dpp v102, v102, v102 quad_perm:[1,0,3,2] row_mask:0xf bank_mask:0xf bound_ctrl:1
	s_waitcnt lgkmcnt(2)
	v_pk_mul_f32 v[84:85], v[116:117], v[68:69]
	v_pk_mul_f32 v[86:87], v[82:83], v[64:65] op_sel:[1,0]
	v_pk_fma_f32 v[84:85], v[118:119], v[70:71], v[84:85]
	v_pk_mul_f32 v[88:89], v[82:83], v[66:67] op_sel:[1,0]
	ds_read_b128 v[80:83], v106 offset:32
	v_add_f32_e32 v92, v84, v85
	v_pk_fma_f32 v[86:87], v[116:117], v[76:77], v[86:87]
	v_pk_mul_f32 v[90:91], v[116:117], v[40:41]
	v_add_f32_dpp v92, v92, v92 quad_perm:[1,0,3,2] row_mask:0xf bank_mask:0xf bound_ctrl:1
	v_pk_fma_f32 v[88:89], v[118:119], v[78:79], v[88:89]
	v_pk_fma_f32 v[90:91], v[118:119], v[42:43], v[90:91]
	s_waitcnt lgkmcnt(2)
; #define YRED4(dst) { \
;           float a0 = b3 ? p2 : p0, a1 = b3 ? p3 : p1; const float s0 = b3 ? p0 : p2, s1 = b3 ? p1 : p3; \
;           a0 += dppf<0x128>(s0); a1 += dppf<0x128>(s1); \
;           float cc = b2 ? a1 : a0; const float dd = b2 ? a0 : a1; \
;           cc += dppf<0x141>(dd); cc += dppf<0xB1>(cc); cc += dppf<0x4E>(cc); dst = cc; }
; __device__ __forceinline__ void phase_scan(KP p) {
;     ...
;         SLD(A, 0); SLD(B, 1);
;         for (int g = 0; g < 8; ++g) {
;           const int st = g * 4;
;           SLD(C, st + 2); vnext = *(const float4*)(vb4 + st + 4);
;           __builtin_amdgcn_sched_barrier(0);
;           if (g > 0) { float yv; YRED4(yv); yb[(st - 4) * 16] = yv; }
;           SCOMP(A, vcur.x, q0);
;           SLD(D, st + 3);
;           __builtin_amdgcn_sched_barrier(0);
;           SCOMP(B, vcur.y, q1);
;           SLD(A, st + 4);
;           __builtin_amdgcn_sched_barrier(0);
;           SCOMP(C, vcur.z, q2);
;           SLD(B, st + 5);
;           __builtin_amdgcn_sched_barrier(0);
;           SCOMP(D, vcur.w, q3);
;           vcur = vnext; p0 = q0; p1 = q1; p2 = q2; p3 = q3;
;         }
	v_mfma_f32_32x32x16_bf16 v[20:35], v[112:115], v[124:127], 0
	v_add_f32_dpp v92, v92, v92 quad_perm:[2,3,0,1] row_mask:0xf bank_mask:0xf bound_ctrl:1
	v_add_f32_e32 v98, v90, v91
	ds_read_b128 v[108:111], v128 offset:5440
	v_add_f32_dpp v92, v92, v92 row_half_mirror row_mask:0xf bank_mask:0xf bound_ctrl:1
	ds_read_b128 v[36:39], v105 offset:11776
	v_add_f32_dpp v102, v102, v102 quad_perm:[2,3,0,1] row_mask:0xf bank_mask:0xf bound_ctrl:1
	v_add_f32_dpp v92, v92, v92 row_mirror row_mask:0xf bank_mask:0xf bound_ctrl:1
	v_pk_fma_f32 v[116:117], v[72:73], v[92:93], v[86:87] op_sel_hi:[1,0,1]
	v_pk_fma_f32 v[118:119], v[74:75], v[92:93], v[88:89] op_sel_hi:[1,0,1]
	ds_write_b32 v107, v102
	s_waitcnt lgkmcnt(3)
	v_pk_mul_f32 v[84:85], v[116:117], v[8:9]
	v_pk_mul_f32 v[86:87], v[80:81], v[4:5] op_sel_hi:[0,1]
	v_pk_fma_f32 v[84:85], v[118:119], v[10:11], v[84:85]
	v_pk_mul_f32 v[88:89], v[80:81], v[6:7] op_sel_hi:[0,1]
	v_add_f32_e32 v92, v84, v85
	v_pk_fma_f32 v[86:87], v[116:117], v[16:17], v[86:87]
	v_pk_mul_f32 v[90:91], v[116:117], v[60:61]
	v_add_f32_dpp v92, v92, v92 quad_perm:[1,0,3,2] row_mask:0xf bank_mask:0xf bound_ctrl:1
	v_pk_fma_f32 v[88:89], v[118:119], v[18:19], v[88:89]
	v_pk_fma_f32 v[90:91], v[118:119], v[62:63], v[90:91]
	s_waitcnt lgkmcnt(2)
	v_mfma_f32_32x32x16_bf16 v[40:55], v[108:111], v[124:127], 0
	v_add_f32_dpp v92, v92, v92 quad_perm:[2,3,0,1] row_mask:0xf bank_mask:0xf bound_ctrl:1
	v_add_f32_e32 v99, v90, v91
	ds_read_b128 v[112:115], v128 offset:5984
	v_cndmask_b32_e64 v100, v98, v96, s[38:39]
	v_cndmask_b32_e64 v102, v96, v98, s[38:39]
	v_add_f32_dpp v92, v92, v92 row_half_mirror row_mask:0xf bank_mask:0xf bound_ctrl:1
	ds_read_b128 v[56:59], v105 offset:13056
	v_cndmask_b32_e64 v101, v99, v97, s[38:39]
	v_cndmask_b32_e64 v103, v97, v99, s[38:39]
	v_add_f32_dpp v92, v92, v92 row_mirror row_mask:0xf bank_mask:0xf bound_ctrl:1
	v_pk_fma_f32 v[116:117], v[12:13], v[92:93], v[86:87] op_sel_hi:[1,0,1]
	v_pk_fma_f32 v[118:119], v[14:15], v[92:93], v[88:89] op_sel_hi:[1,0,1]
	s_waitcnt lgkmcnt(3)
	v_pk_mul_f32 v[84:85], v[116:117], v[28:29]
	v_pk_mul_f32 v[86:87], v[80:81], v[24:25] op_sel:[1,0]
	v_pk_fma_f32 v[84:85], v[118:119], v[30:31], v[84:85]
	v_pk_mul_f32 v[88:89], v[80:81], v[26:27] op_sel:[1,0]
	v_add_f32_e32 v92, v84, v85
	v_pk_fma_f32 v[86:87], v[116:117], v[36:37], v[86:87]
	v_pk_mul_f32 v[90:91], v[116:117], v[0:1]
	v_add_f32_dpp v92, v92, v92 quad_perm:[1,0,3,2] row_mask:0xf bank_mask:0xf bound_ctrl:1
	v_pk_fma_f32 v[88:89], v[118:119], v[38:39], v[88:89]
	v_pk_fma_f32 v[90:91], v[118:119], v[2:3], v[90:91]
	s_waitcnt lgkmcnt(1)
	v_mfma_f32_32x32x16_bf16 v[60:75], v[112:115], v[124:127], 0
	v_add_f32_dpp v92, v92, v92 quad_perm:[2,3,0,1] row_mask:0xf bank_mask:0xf bound_ctrl:1
	v_add_f32_e32 v96, v90, v91
	ds_read_b128 v[108:111], v128 offset:6528
	v_add_f32_dpp v102, v102, v100 row_ror:8 row_mask:0xf bank_mask:0xf bound_ctrl:1
	v_add_f32_dpp v92, v92, v92 row_half_mirror row_mask:0xf bank_mask:0xf bound_ctrl:1
	ds_read_b128 v[76:79], v105 offset:14336
	v_add_f32_dpp v103, v103, v101 row_ror:8 row_mask:0xf bank_mask:0xf bound_ctrl:1
	v_add_f32_dpp v92, v92, v92 row_mirror row_mask:0xf bank_mask:0xf bound_ctrl:1
	v_cndmask_b32_e64 v104, v103, v102, s[40:41]
	v_cndmask_b32_e64 v102, v102, v103, s[40:41]
	v_pk_fma_f32 v[116:117], v[32:33], v[92:93], v[86:87] op_sel_hi:[1,0,1]
	v_pk_fma_f32 v[118:119], v[34:35], v[92:93], v[88:89] op_sel_hi:[1,0,1]
	s_waitcnt lgkmcnt(2)
	v_pk_mul_f32 v[84:85], v[116:117], v[48:49]
	v_pk_mul_f32 v[86:87], v[82:83], v[44:45] op_sel_hi:[0,1]
	v_pk_fma_f32 v[84:85], v[118:119], v[50:51], v[84:85]
	v_pk_mul_f32 v[88:89], v[82:83], v[46:47] op_sel_hi:[0,1]
	v_add_f32_e32 v92, v84, v85
	v_pk_fma_f32 v[86:87], v[116:117], v[56:57], v[86:87]
	v_pk_mul_f32 v[90:91], v[116:117], v[20:21]
	v_add_f32_dpp v92, v92, v92 quad_perm:[1,0,3,2] row_mask:0xf bank_mask:0xf bound_ctrl:1
	v_pk_fma_f32 v[88:89], v[118:119], v[58:59], v[88:89]
	v_pk_fma_f32 v[90:91], v[118:119], v[22:23], v[90:91]
	s_waitcnt lgkmcnt(1)
	v_mfma_f32_32x32x16_bf16 v[0:15], v[108:111], v[124:127], 0
	v_add_f32_dpp v92, v92, v92 quad_perm:[2,3,0,1] row_mask:0xf bank_mask:0xf bound_ctrl:1
	v_add_f32_e32 v97, v90, v91
	ds_read_b128 v[112:115], v128 offset:7072
	v_add_f32_dpp v92, v92, v92 row_half_mirror row_mask:0xf bank_mask:0xf bound_ctrl:1
	ds_read_b128 v[16:19], v105 offset:15616
	v_add_f32_dpp v102, v102, v104 row_half_mirror row_mask:0xf bank_mask:0xf bound_ctrl:1
	v_add_f32_dpp v92, v92, v92 row_mirror row_mask:0xf bank_mask:0xf bound_ctrl:1
	v_pk_fma_f32 v[116:117], v[52:53], v[92:93], v[86:87] op_sel_hi:[1,0,1]
	v_pk_fma_f32 v[118:119], v[54:55], v[92:93], v[88:89] op_sel_hi:[1,0,1]
	v_add_f32_dpp v102, v102, v102 quad_perm:[1,0,3,2] row_mask:0xf bank_mask:0xf bound_ctrl:1
	s_waitcnt lgkmcnt(2)
	v_pk_mul_f32 v[84:85], v[116:117], v[68:69]
	v_pk_mul_f32 v[86:87], v[82:83], v[64:65] op_sel:[1,0]
	v_pk_fma_f32 v[84:85], v[118:119], v[70:71], v[84:85]
	v_pk_mul_f32 v[88:89], v[82:83], v[66:67] op_sel:[1,0]
	ds_read_b128 v[80:83], v106 offset:48
	v_add_f32_e32 v92, v84, v85
	v_pk_fma_f32 v[86:87], v[116:117], v[76:77], v[86:87]
	v_pk_mul_f32 v[90:91], v[116:117], v[40:41]
	v_add_f32_dpp v92, v92, v92 quad_perm:[1,0,3,2] row_mask:0xf bank_mask:0xf bound_ctrl:1
	v_pk_fma_f32 v[88:89], v[118:119], v[78:79], v[88:89]
	v_pk_fma_f32 v[90:91], v[118:119], v[42:43], v[90:91]
	s_waitcnt lgkmcnt(2)
; #define YRED4(dst) { \
;           float a0 = b3 ? p2 : p0, a1 = b3 ? p3 : p1; const float s0 = b3 ? p0 : p2, s1 = b3 ? p1 : p3; \
;           a0 += dppf<0x128>(s0); a1 += dppf<0x128>(s1); \
;           float cc = b2 ? a1 : a0; const float dd = b2 ? a0 : a1; \
;           cc += dppf<0x141>(dd); cc += dppf<0xB1>(cc); cc += dppf<0x4E>(cc); dst = cc; }
; __device__ __forceinline__ void phase_scan(KP p) {
;     ...
;         SLD(A, 0); SLD(B, 1);
;         for (int g = 0; g < 8; ++g) {
;           const int st = g * 4;
;           SLD(C, st + 2); vnext = *(const float4*)(vb4 + st + 4);
;           __builtin_amdgcn_sched_barrier(0);
;           if (g > 0) { float yv; YRED4(yv); yb[(st - 4) * 16] = yv; }
;           SCOMP(A, vcur.x, q0);
;           SLD(D, st + 3);
;           __builtin_amdgcn_sched_barrier(0);
;           SCOMP(B, vcur.y, q1);
;           SLD(A, st + 4);
;           __builtin_amdgcn_sched_barrier(0);
;           SCOMP(C, vcur.z, q2);
;           SLD(B, st + 5);
;           __builtin_amdgcn_sched_barrier(0);
;           SCOMP(D, vcur.w, q3);
;           vcur = vnext; p0 = q0; p1 = q1; p2 = q2; p3 = q3;
;         }
	v_mfma_f32_32x32x16_bf16 v[20:35], v[112:115], v[124:127], 0
	v_add_f32_dpp v92, v92, v92 quad_perm:[2,3,0,1] row_mask:0xf bank_mask:0xf bound_ctrl:1
	v_add_f32_e32 v98, v90, v91
	ds_read_b128 v[108:111], v128 offset:7616
	v_add_f32_dpp v92, v92, v92 row_half_mirror row_mask:0xf bank_mask:0xf bound_ctrl:1
	ds_read_b128 v[36:39], v105 offset:16896
	v_add_f32_dpp v102, v102, v102 quad_perm:[2,3,0,1] row_mask:0xf bank_mask:0xf bound_ctrl:1
	v_add_f32_dpp v92, v92, v92 row_mirror row_mask:0xf bank_mask:0xf bound_ctrl:1
	v_pk_fma_f32 v[116:117], v[72:73], v[92:93], v[86:87] op_sel_hi:[1,0,1]
	v_pk_fma_f32 v[118:119], v[74:75], v[92:93], v[88:89] op_sel_hi:[1,0,1]
	ds_write_b32 v107, v102 offset:256
	s_waitcnt lgkmcnt(3)
	v_pk_mul_f32 v[84:85], v[116:117], v[8:9]
	v_pk_mul_f32 v[86:87], v[80:81], v[4:5] op_sel_hi:[0,1]
	v_pk_fma_f32 v[84:85], v[118:119], v[10:11], v[84:85]
	v_pk_mul_f32 v[88:89], v[80:81], v[6:7] op_sel_hi:[0,1]
	v_add_f32_e32 v92, v84, v85
	v_pk_fma_f32 v[86:87], v[116:117], v[16:17], v[86:87]
	v_pk_mul_f32 v[90:91], v[116:117], v[60:61]
	v_add_f32_dpp v92, v92, v92 quad_perm:[1,0,3,2] row_mask:0xf bank_mask:0xf bound_ctrl:1
	v_pk_fma_f32 v[88:89], v[118:119], v[18:19], v[88:89]
	v_pk_fma_f32 v[90:91], v[118:119], v[62:63], v[90:91]
	s_waitcnt lgkmcnt(2)
	v_mfma_f32_32x32x16_bf16 v[40:55], v[108:111], v[124:127], 0
	v_add_f32_dpp v92, v92, v92 quad_perm:[2,3,0,1] row_mask:0xf bank_mask:0xf bound_ctrl:1
	v_add_f32_e32 v99, v90, v91
	ds_read_b128 v[112:115], v128 offset:8160
	v_cndmask_b32_e64 v100, v98, v96, s[38:39]
	v_cndmask_b32_e64 v102, v96, v98, s[38:39]
	v_add_f32_dpp v92, v92, v92 row_half_mirror row_mask:0xf bank_mask:0xf bound_ctrl:1
	ds_read_b128 v[56:59], v105 offset:18176
	v_cndmask_b32_e64 v101, v99, v97, s[38:39]
	v_cndmask_b32_e64 v103, v97, v99, s[38:39]
	v_add_f32_dpp v92, v92, v92 row_mirror row_mask:0xf bank_mask:0xf bound_ctrl:1
	v_pk_fma_f32 v[116:117], v[12:13], v[92:93], v[86:87] op_sel_hi:[1,0,1]
	v_pk_fma_f32 v[118:119], v[14:15], v[92:93], v[88:89] op_sel_hi:[1,0,1]
	s_waitcnt lgkmcnt(3)
	v_pk_mul_f32 v[84:85], v[116:117], v[28:29]
	v_pk_mul_f32 v[86:87], v[80:81], v[24:25] op_sel:[1,0]
	v_pk_fma_f32 v[84:85], v[118:119], v[30:31], v[84:85]
	v_pk_mul_f32 v[88:89], v[80:81], v[26:27] op_sel:[1,0]
	v_add_f32_e32 v92, v84, v85
	v_pk_fma_f32 v[86:87], v[116:117], v[36:37], v[86:87]
	v_pk_mul_f32 v[90:91], v[116:117], v[0:1]
	v_add_f32_dpp v92, v92, v92 quad_perm:[1,0,3,2] row_mask:0xf bank_mask:0xf bound_ctrl:1
	v_pk_fma_f32 v[88:89], v[118:119], v[38:39], v[88:89]
	v_pk_fma_f32 v[90:91], v[118:119], v[2:3], v[90:91]
	s_waitcnt lgkmcnt(1)
	v_mfma_f32_32x32x16_bf16 v[60:75], v[112:115], v[124:127], 0
	v_add_f32_dpp v92, v92, v92 quad_perm:[2,3,0,1] row_mask:0xf bank_mask:0xf bound_ctrl:1
	v_add_f32_e32 v96, v90, v91
	ds_read_b128 v[108:111], v128 offset:8704
	v_add_f32_dpp v102, v102, v100 row_ror:8 row_mask:0xf bank_mask:0xf bound_ctrl:1
	v_add_f32_dpp v92, v92, v92 row_half_mirror row_mask:0xf bank_mask:0xf bound_ctrl:1
	ds_read_b128 v[76:79], v105 offset:19456
	v_add_f32_dpp v103, v103, v101 row_ror:8 row_mask:0xf bank_mask:0xf bound_ctrl:1
	v_add_f32_dpp v92, v92, v92 row_mirror row_mask:0xf bank_mask:0xf bound_ctrl:1
	v_cndmask_b32_e64 v104, v103, v102, s[40:41]
	v_cndmask_b32_e64 v102, v102, v103, s[40:41]
	v_pk_fma_f32 v[116:117], v[32:33], v[92:93], v[86:87] op_sel_hi:[1,0,1]
	v_pk_fma_f32 v[118:119], v[34:35], v[92:93], v[88:89] op_sel_hi:[1,0,1]
	s_waitcnt lgkmcnt(2)
	v_pk_mul_f32 v[84:85], v[116:117], v[48:49]
	v_pk_mul_f32 v[86:87], v[82:83], v[44:45] op_sel_hi:[0,1]
	v_pk_fma_f32 v[84:85], v[118:119], v[50:51], v[84:85]
	v_pk_mul_f32 v[88:89], v[82:83], v[46:47] op_sel_hi:[0,1]
	v_add_f32_e32 v92, v84, v85
	v_pk_fma_f32 v[86:87], v[116:117], v[56:57], v[86:87]
	v_pk_mul_f32 v[90:91], v[116:117], v[20:21]
	v_add_f32_dpp v92, v92, v92 quad_perm:[1,0,3,2] row_mask:0xf bank_mask:0xf bound_ctrl:1
	v_pk_fma_f32 v[88:89], v[118:119], v[58:59], v[88:89]
	v_pk_fma_f32 v[90:91], v[118:119], v[22:23], v[90:91]
	s_waitcnt lgkmcnt(1)
	v_mfma_f32_32x32x16_bf16 v[0:15], v[108:111], v[124:127], 0
	v_add_f32_dpp v92, v92, v92 quad_perm:[2,3,0,1] row_mask:0xf bank_mask:0xf bound_ctrl:1
	v_add_f32_e32 v97, v90, v91
	ds_read_b128 v[112:115], v128 offset:9248
	v_add_f32_dpp v92, v92, v92 row_half_mirror row_mask:0xf bank_mask:0xf bound_ctrl:1
	ds_read_b128 v[16:19], v105 offset:20736
	v_add_f32_dpp v102, v102, v104 row_half_mirror row_mask:0xf bank_mask:0xf bound_ctrl:1
	v_add_f32_dpp v92, v92, v92 row_mirror row_mask:0xf bank_mask:0xf bound_ctrl:1
	v_pk_fma_f32 v[116:117], v[52:53], v[92:93], v[86:87] op_sel_hi:[1,0,1]
	v_pk_fma_f32 v[118:119], v[54:55], v[92:93], v[88:89] op_sel_hi:[1,0,1]
	v_add_f32_dpp v102, v102, v102 quad_perm:[1,0,3,2] row_mask:0xf bank_mask:0xf bound_ctrl:1
	s_waitcnt lgkmcnt(2)
	v_pk_mul_f32 v[84:85], v[116:117], v[68:69]
	v_pk_mul_f32 v[86:87], v[82:83], v[64:65] op_sel:[1,0]
	v_pk_fma_f32 v[84:85], v[118:119], v[70:71], v[84:85]
	v_pk_mul_f32 v[88:89], v[82:83], v[66:67] op_sel:[1,0]
	ds_read_b128 v[80:83], v106 offset:64
	v_add_f32_e32 v92, v84, v85
	v_pk_fma_f32 v[86:87], v[116:117], v[76:77], v[86:87]
	v_pk_mul_f32 v[90:91], v[116:117], v[40:41]
	v_add_f32_dpp v92, v92, v92 quad_perm:[1,0,3,2] row_mask:0xf bank_mask:0xf bound_ctrl:1
	v_pk_fma_f32 v[88:89], v[118:119], v[78:79], v[88:89]
	v_pk_fma_f32 v[90:91], v[118:119], v[42:43], v[90:91]
	s_waitcnt lgkmcnt(2)
; #define YRED4(dst) { \
;           float a0 = b3 ? p2 : p0, a1 = b3 ? p3 : p1; const float s0 = b3 ? p0 : p2, s1 = b3 ? p1 : p3; \
;           a0 += dppf<0x128>(s0); a1 += dppf<0x128>(s1); \
;           float cc = b2 ? a1 : a0; const float dd = b2 ? a0 : a1; \
;           cc += dppf<0x141>(dd); cc += dppf<0xB1>(cc); cc += dppf<0x4E>(cc); dst = cc; }
; __device__ __forceinline__ void phase_scan(KP p) {
;     ...
;         SLD(A, 0); SLD(B, 1);
;         for (int g = 0; g < 8; ++g) {
;           const int st = g * 4;
;           SLD(C, st + 2); vnext = *(const float4*)(vb4 + st + 4);
;           __builtin_amdgcn_sched_barrier(0);
;           if (g > 0) { float yv; YRED4(yv); yb[(st - 4) * 16] = yv; }
;           SCOMP(A, vcur.x, q0);
;           SLD(D, st + 3);
;           __builtin_amdgcn_sched_barrier(0);
;           SCOMP(B, vcur.y, q1);
;           SLD(A, st + 4);
;           __builtin_amdgcn_sched_barrier(0);
;           SCOMP(C, vcur.z, q2);
;           SLD(B, st + 5);
;           __builtin_amdgcn_sched_barrier(0);
;           SCOMP(D, vcur.w, q3);
;           vcur = vnext; p0 = q0; p1 = q1; p2 = q2; p3 = q3;
;         }
	v_mfma_f32_32x32x16_bf16 v[20:35], v[112:115], v[124:127], 0
	v_add_f32_dpp v92, v92, v92 quad_perm:[2,3,0,1] row_mask:0xf bank_mask:0xf bound_ctrl:1
	v_add_f32_e32 v98, v90, v91
	ds_read_b128 v[108:111], v128 offset:9792
	v_add_f32_dpp v92, v92, v92 row_half_mirror row_mask:0xf bank_mask:0xf bound_ctrl:1
	ds_read_b128 v[36:39], v105 offset:22016
	v_add_f32_dpp v102, v102, v102 quad_perm:[2,3,0,1] row_mask:0xf bank_mask:0xf bound_ctrl:1
	v_add_f32_dpp v92, v92, v92 row_mirror row_mask:0xf bank_mask:0xf bound_ctrl:1
	v_pk_fma_f32 v[116:117], v[72:73], v[92:93], v[86:87] op_sel_hi:[1,0,1]
	v_pk_fma_f32 v[118:119], v[74:75], v[92:93], v[88:89] op_sel_hi:[1,0,1]
	ds_write_b32 v107, v102 offset:512
	s_waitcnt lgkmcnt(3)
	v_pk_mul_f32 v[84:85], v[116:117], v[8:9]
	v_pk_mul_f32 v[86:87], v[80:81], v[4:5] op_sel_hi:[0,1]
	v_pk_fma_f32 v[84:85], v[118:119], v[10:11], v[84:85]
	v_pk_mul_f32 v[88:89], v[80:81], v[6:7] op_sel_hi:[0,1]
	v_add_f32_e32 v92, v84, v85
	v_pk_fma_f32 v[86:87], v[116:117], v[16:17], v[86:87]
	v_pk_mul_f32 v[90:91], v[116:117], v[60:61]
	v_add_f32_dpp v92, v92, v92 quad_perm:[1,0,3,2] row_mask:0xf bank_mask:0xf bound_ctrl:1
	v_pk_fma_f32 v[88:89], v[118:119], v[18:19], v[88:89]
	v_pk_fma_f32 v[90:91], v[118:119], v[62:63], v[90:91]
	s_waitcnt lgkmcnt(2)
	v_mfma_f32_32x32x16_bf16 v[40:55], v[108:111], v[124:127], 0
	v_add_f32_dpp v92, v92, v92 quad_perm:[2,3,0,1] row_mask:0xf bank_mask:0xf bound_ctrl:1
	v_add_f32_e32 v99, v90, v91
	ds_read_b128 v[112:115], v128 offset:10336
	v_cndmask_b32_e64 v100, v98, v96, s[38:39]
	v_cndmask_b32_e64 v102, v96, v98, s[38:39]
	v_add_f32_dpp v92, v92, v92 row_half_mirror row_mask:0xf bank_mask:0xf bound_ctrl:1
	ds_read_b128 v[56:59], v105 offset:23296
	v_cndmask_b32_e64 v101, v99, v97, s[38:39]
	v_cndmask_b32_e64 v103, v97, v99, s[38:39]
	v_add_f32_dpp v92, v92, v92 row_mirror row_mask:0xf bank_mask:0xf bound_ctrl:1
	v_pk_fma_f32 v[116:117], v[12:13], v[92:93], v[86:87] op_sel_hi:[1,0,1]
	v_pk_fma_f32 v[118:119], v[14:15], v[92:93], v[88:89] op_sel_hi:[1,0,1]
	s_waitcnt lgkmcnt(3)
	v_pk_mul_f32 v[84:85], v[116:117], v[28:29]
	v_pk_mul_f32 v[86:87], v[80:81], v[24:25] op_sel:[1,0]
	v_pk_fma_f32 v[84:85], v[118:119], v[30:31], v[84:85]
	v_pk_mul_f32 v[88:89], v[80:81], v[26:27] op_sel:[1,0]
	v_add_f32_e32 v92, v84, v85
	v_pk_fma_f32 v[86:87], v[116:117], v[36:37], v[86:87]
	v_pk_mul_f32 v[90:91], v[116:117], v[0:1]
	v_add_f32_dpp v92, v92, v92 quad_perm:[1,0,3,2] row_mask:0xf bank_mask:0xf bound_ctrl:1
	v_pk_fma_f32 v[88:89], v[118:119], v[38:39], v[88:89]
	v_pk_fma_f32 v[90:91], v[118:119], v[2:3], v[90:91]
	s_waitcnt lgkmcnt(1)
	v_mfma_f32_32x32x16_bf16 v[60:75], v[112:115], v[124:127], 0
	v_add_f32_dpp v92, v92, v92 quad_perm:[2,3,0,1] row_mask:0xf bank_mask:0xf bound_ctrl:1
	v_add_f32_e32 v96, v90, v91
	ds_read_b128 v[108:111], v128 offset:10880
	v_add_f32_dpp v102, v102, v100 row_ror:8 row_mask:0xf bank_mask:0xf bound_ctrl:1
	v_add_f32_dpp v92, v92, v92 row_half_mirror row_mask:0xf bank_mask:0xf bound_ctrl:1
	ds_read_b128 v[76:79], v105 offset:24576
	v_add_f32_dpp v103, v103, v101 row_ror:8 row_mask:0xf bank_mask:0xf bound_ctrl:1
	v_add_f32_dpp v92, v92, v92 row_mirror row_mask:0xf bank_mask:0xf bound_ctrl:1
	v_cndmask_b32_e64 v104, v103, v102, s[40:41]
	v_cndmask_b32_e64 v102, v102, v103, s[40:41]
	v_pk_fma_f32 v[116:117], v[32:33], v[92:93], v[86:87] op_sel_hi:[1,0,1]
	v_pk_fma_f32 v[118:119], v[34:35], v[92:93], v[88:89] op_sel_hi:[1,0,1]
	s_waitcnt lgkmcnt(2)
	v_pk_mul_f32 v[84:85], v[116:117], v[48:49]
	v_pk_mul_f32 v[86:87], v[82:83], v[44:45] op_sel_hi:[0,1]
	v_pk_fma_f32 v[84:85], v[118:119], v[50:51], v[84:85]
	v_pk_mul_f32 v[88:89], v[82:83], v[46:47] op_sel_hi:[0,1]
	v_add_f32_e32 v92, v84, v85
	v_pk_fma_f32 v[86:87], v[116:117], v[56:57], v[86:87]
	v_pk_mul_f32 v[90:91], v[116:117], v[20:21]
	v_add_f32_dpp v92, v92, v92 quad_perm:[1,0,3,2] row_mask:0xf bank_mask:0xf bound_ctrl:1
	v_pk_fma_f32 v[88:89], v[118:119], v[58:59], v[88:89]
	v_pk_fma_f32 v[90:91], v[118:119], v[22:23], v[90:91]
	s_waitcnt lgkmcnt(1)
	v_mfma_f32_32x32x16_bf16 v[0:15], v[108:111], v[124:127], 0
	v_add_f32_dpp v92, v92, v92 quad_perm:[2,3,0,1] row_mask:0xf bank_mask:0xf bound_ctrl:1
	v_add_f32_e32 v97, v90, v91
	ds_read_b128 v[112:115], v128 offset:11424
	v_add_f32_dpp v92, v92, v92 row_half_mirror row_mask:0xf bank_mask:0xf bound_ctrl:1
	ds_read_b128 v[16:19], v105 offset:25856
	v_add_f32_dpp v102, v102, v104 row_half_mirror row_mask:0xf bank_mask:0xf bound_ctrl:1
	v_add_f32_dpp v92, v92, v92 row_mirror row_mask:0xf bank_mask:0xf bound_ctrl:1
	v_pk_fma_f32 v[116:117], v[52:53], v[92:93], v[86:87] op_sel_hi:[1,0,1]
	v_pk_fma_f32 v[118:119], v[54:55], v[92:93], v[88:89] op_sel_hi:[1,0,1]
	v_add_f32_dpp v102, v102, v102 quad_perm:[1,0,3,2] row_mask:0xf bank_mask:0xf bound_ctrl:1
	s_waitcnt lgkmcnt(2)
	v_pk_mul_f32 v[84:85], v[116:117], v[68:69]
	v_pk_mul_f32 v[86:87], v[82:83], v[64:65] op_sel:[1,0]
	v_pk_fma_f32 v[84:85], v[118:119], v[70:71], v[84:85]
	v_pk_mul_f32 v[88:89], v[82:83], v[66:67] op_sel:[1,0]
	ds_read_b128 v[80:83], v106 offset:80
	v_add_f32_e32 v92, v84, v85
	v_pk_fma_f32 v[86:87], v[116:117], v[76:77], v[86:87]
	v_pk_mul_f32 v[90:91], v[116:117], v[40:41]
	v_add_f32_dpp v92, v92, v92 quad_perm:[1,0,3,2] row_mask:0xf bank_mask:0xf bound_ctrl:1
	v_pk_fma_f32 v[88:89], v[118:119], v[78:79], v[88:89]
	v_pk_fma_f32 v[90:91], v[118:119], v[42:43], v[90:91]
	s_waitcnt lgkmcnt(2)
; #define YRED4(dst) { \
;           float a0 = b3 ? p2 : p0, a1 = b3 ? p3 : p1; const float s0 = b3 ? p0 : p2, s1 = b3 ? p1 : p3; \
;           a0 += dppf<0x128>(s0); a1 += dppf<0x128>(s1); \
;           float cc = b2 ? a1 : a0; const float dd = b2 ? a0 : a1; \
;           cc += dppf<0x141>(dd); cc += dppf<0xB1>(cc); cc += dppf<0x4E>(cc); dst = cc; }
; __device__ __forceinline__ void phase_scan(KP p) {
;     ...
;         SLD(A, 0); SLD(B, 1);
;         for (int g = 0; g < 8; ++g) {
;           const int st = g * 4;
;           SLD(C, st + 2); vnext = *(const float4*)(vb4 + st + 4);
;           __builtin_amdgcn_sched_barrier(0);
;           if (g > 0) { float yv; YRED4(yv); yb[(st - 4) * 16] = yv; }
;           SCOMP(A, vcur.x, q0);
;           SLD(D, st + 3);
;           __builtin_amdgcn_sched_barrier(0);
;           SCOMP(B, vcur.y, q1);
;           SLD(A, st + 4);
;           __builtin_amdgcn_sched_barrier(0);
;           SCOMP(C, vcur.z, q2);
;           SLD(B, st + 5);
;           __builtin_amdgcn_sched_barrier(0);
;           SCOMP(D, vcur.w, q3);
;           vcur = vnext; p0 = q0; p1 = q1; p2 = q2; p3 = q3;
;         }
	v_mfma_f32_32x32x16_bf16 v[20:35], v[112:115], v[124:127], 0
	v_add_f32_dpp v92, v92, v92 quad_perm:[2,3,0,1] row_mask:0xf bank_mask:0xf bound_ctrl:1
	v_add_f32_e32 v98, v90, v91
	ds_read_b128 v[108:111], v128 offset:11968
	v_add_f32_dpp v92, v92, v92 row_half_mirror row_mask:0xf bank_mask:0xf bound_ctrl:1
	ds_read_b128 v[36:39], v105 offset:27136
	v_add_f32_dpp v102, v102, v102 quad_perm:[2,3,0,1] row_mask:0xf bank_mask:0xf bound_ctrl:1
	v_add_f32_dpp v92, v92, v92 row_mirror row_mask:0xf bank_mask:0xf bound_ctrl:1
	v_pk_fma_f32 v[116:117], v[72:73], v[92:93], v[86:87] op_sel_hi:[1,0,1]
	v_pk_fma_f32 v[118:119], v[74:75], v[92:93], v[88:89] op_sel_hi:[1,0,1]
	ds_write_b32 v107, v102 offset:768
	s_waitcnt lgkmcnt(3)
	v_pk_mul_f32 v[84:85], v[116:117], v[8:9]
	v_pk_mul_f32 v[86:87], v[80:81], v[4:5] op_sel_hi:[0,1]
	v_pk_fma_f32 v[84:85], v[118:119], v[10:11], v[84:85]
	v_pk_mul_f32 v[88:89], v[80:81], v[6:7] op_sel_hi:[0,1]
	v_add_f32_e32 v92, v84, v85
	v_pk_fma_f32 v[86:87], v[116:117], v[16:17], v[86:87]
	v_pk_mul_f32 v[90:91], v[116:117], v[60:61]
	v_add_f32_dpp v92, v92, v92 quad_perm:[1,0,3,2] row_mask:0xf bank_mask:0xf bound_ctrl:1
	v_pk_fma_f32 v[88:89], v[118:119], v[18:19], v[88:89]
	v_pk_fma_f32 v[90:91], v[118:119], v[62:63], v[90:91]
	s_waitcnt lgkmcnt(2)
	v_mfma_f32_32x32x16_bf16 v[40:55], v[108:111], v[124:127], 0
	v_add_f32_dpp v92, v92, v92 quad_perm:[2,3,0,1] row_mask:0xf bank_mask:0xf bound_ctrl:1
	v_add_f32_e32 v99, v90, v91
	ds_read_b128 v[112:115], v128 offset:12512
	v_cndmask_b32_e64 v100, v98, v96, s[38:39]
	v_cndmask_b32_e64 v102, v96, v98, s[38:39]
	v_add_f32_dpp v92, v92, v92 row_half_mirror row_mask:0xf bank_mask:0xf bound_ctrl:1
	ds_read_b128 v[56:59], v105 offset:28416
	v_cndmask_b32_e64 v101, v99, v97, s[38:39]
	v_cndmask_b32_e64 v103, v97, v99, s[38:39]
	v_add_f32_dpp v92, v92, v92 row_mirror row_mask:0xf bank_mask:0xf bound_ctrl:1
	v_pk_fma_f32 v[116:117], v[12:13], v[92:93], v[86:87] op_sel_hi:[1,0,1]
	v_pk_fma_f32 v[118:119], v[14:15], v[92:93], v[88:89] op_sel_hi:[1,0,1]
	s_waitcnt lgkmcnt(3)
	v_pk_mul_f32 v[84:85], v[116:117], v[28:29]
	v_pk_mul_f32 v[86:87], v[80:81], v[24:25] op_sel:[1,0]
	v_pk_fma_f32 v[84:85], v[118:119], v[30:31], v[84:85]
	v_pk_mul_f32 v[88:89], v[80:81], v[26:27] op_sel:[1,0]
	v_add_f32_e32 v92, v84, v85
	v_pk_fma_f32 v[86:87], v[116:117], v[36:37], v[86:87]
	v_pk_mul_f32 v[90:91], v[116:117], v[0:1]
	v_add_f32_dpp v92, v92, v92 quad_perm:[1,0,3,2] row_mask:0xf bank_mask:0xf bound_ctrl:1
	v_pk_fma_f32 v[88:89], v[118:119], v[38:39], v[88:89]
	v_pk_fma_f32 v[90:91], v[118:119], v[2:3], v[90:91]
	s_waitcnt lgkmcnt(1)
	v_mfma_f32_32x32x16_bf16 v[60:75], v[112:115], v[124:127], 0
	v_add_f32_dpp v92, v92, v92 quad_perm:[2,3,0,1] row_mask:0xf bank_mask:0xf bound_ctrl:1
	v_add_f32_e32 v96, v90, v91
	ds_read_b128 v[108:111], v128 offset:13056
	v_add_f32_dpp v102, v102, v100 row_ror:8 row_mask:0xf bank_mask:0xf bound_ctrl:1
	v_add_f32_dpp v92, v92, v92 row_half_mirror row_mask:0xf bank_mask:0xf bound_ctrl:1
	ds_read_b128 v[76:79], v105 offset:29696
	v_add_f32_dpp v103, v103, v101 row_ror:8 row_mask:0xf bank_mask:0xf bound_ctrl:1
	v_add_f32_dpp v92, v92, v92 row_mirror row_mask:0xf bank_mask:0xf bound_ctrl:1
	v_cndmask_b32_e64 v104, v103, v102, s[40:41]
	v_cndmask_b32_e64 v102, v102, v103, s[40:41]
	v_pk_fma_f32 v[116:117], v[32:33], v[92:93], v[86:87] op_sel_hi:[1,0,1]
	v_pk_fma_f32 v[118:119], v[34:35], v[92:93], v[88:89] op_sel_hi:[1,0,1]
	s_waitcnt lgkmcnt(2)
	v_pk_mul_f32 v[84:85], v[116:117], v[48:49]
	v_pk_mul_f32 v[86:87], v[82:83], v[44:45] op_sel_hi:[0,1]
	v_pk_fma_f32 v[84:85], v[118:119], v[50:51], v[84:85]
	v_pk_mul_f32 v[88:89], v[82:83], v[46:47] op_sel_hi:[0,1]
	v_add_f32_e32 v92, v84, v85
	v_pk_fma_f32 v[86:87], v[116:117], v[56:57], v[86:87]
	v_pk_mul_f32 v[90:91], v[116:117], v[20:21]
	v_add_f32_dpp v92, v92, v92 quad_perm:[1,0,3,2] row_mask:0xf bank_mask:0xf bound_ctrl:1
	v_pk_fma_f32 v[88:89], v[118:119], v[58:59], v[88:89]
	v_pk_fma_f32 v[90:91], v[118:119], v[22:23], v[90:91]
	s_waitcnt lgkmcnt(1)
	v_mfma_f32_32x32x16_bf16 v[0:15], v[108:111], v[124:127], 0
	v_add_f32_dpp v92, v92, v92 quad_perm:[2,3,0,1] row_mask:0xf bank_mask:0xf bound_ctrl:1
	v_add_f32_e32 v97, v90, v91
	ds_read_b128 v[112:115], v128 offset:13600
	v_add_f32_dpp v92, v92, v92 row_half_mirror row_mask:0xf bank_mask:0xf bound_ctrl:1
	ds_read_b128 v[16:19], v105 offset:30976
	v_add_f32_dpp v102, v102, v104 row_half_mirror row_mask:0xf bank_mask:0xf bound_ctrl:1
	v_add_f32_dpp v92, v92, v92 row_mirror row_mask:0xf bank_mask:0xf bound_ctrl:1
	v_pk_fma_f32 v[116:117], v[52:53], v[92:93], v[86:87] op_sel_hi:[1,0,1]
	v_pk_fma_f32 v[118:119], v[54:55], v[92:93], v[88:89] op_sel_hi:[1,0,1]
	v_add_f32_dpp v102, v102, v102 quad_perm:[1,0,3,2] row_mask:0xf bank_mask:0xf bound_ctrl:1
	s_waitcnt lgkmcnt(2)
	v_pk_mul_f32 v[84:85], v[116:117], v[68:69]
	v_pk_mul_f32 v[86:87], v[82:83], v[64:65] op_sel:[1,0]
	v_pk_fma_f32 v[84:85], v[118:119], v[70:71], v[84:85]
	v_pk_mul_f32 v[88:89], v[82:83], v[66:67] op_sel:[1,0]
	ds_read_b128 v[80:83], v106 offset:96
	v_add_f32_e32 v92, v84, v85
	v_pk_fma_f32 v[86:87], v[116:117], v[76:77], v[86:87]
	v_pk_mul_f32 v[90:91], v[116:117], v[40:41]
	v_add_f32_dpp v92, v92, v92 quad_perm:[1,0,3,2] row_mask:0xf bank_mask:0xf bound_ctrl:1
	v_pk_fma_f32 v[88:89], v[118:119], v[78:79], v[88:89]
	v_pk_fma_f32 v[90:91], v[118:119], v[42:43], v[90:91]
	s_waitcnt lgkmcnt(2)
; #define YRED4(dst) { \
;           float a0 = b3 ? p2 : p0, a1 = b3 ? p3 : p1; const float s0 = b3 ? p0 : p2, s1 = b3 ? p1 : p3; \
;           a0 += dppf<0x128>(s0); a1 += dppf<0x128>(s1); \
;           float cc = b2 ? a1 : a0; const float dd = b2 ? a0 : a1; \
;           cc += dppf<0x141>(dd); cc += dppf<0xB1>(cc); cc += dppf<0x4E>(cc); dst = cc; }
; __device__ __forceinline__ void phase_scan(KP p) {
;     ...
;         SLD(A, 0); SLD(B, 1);
;         for (int g = 0; g < 8; ++g) {
;           const int st = g * 4;
;           SLD(C, st + 2); vnext = *(const float4*)(vb4 + st + 4);
;           __builtin_amdgcn_sched_barrier(0);
;           if (g > 0) { float yv; YRED4(yv); yb[(st - 4) * 16] = yv; }
;           SCOMP(A, vcur.x, q0);
;           SLD(D, st + 3);
;           __builtin_amdgcn_sched_barrier(0);
;           SCOMP(B, vcur.y, q1);
;           SLD(A, st + 4);
;           __builtin_amdgcn_sched_barrier(0);
;           SCOMP(C, vcur.z, q2);
;           SLD(B, st + 5);
;           __builtin_amdgcn_sched_barrier(0);
;           SCOMP(D, vcur.w, q3);
;           vcur = vnext; p0 = q0; p1 = q1; p2 = q2; p3 = q3;
;         }
	v_mfma_f32_32x32x16_bf16 v[20:35], v[112:115], v[124:127], 0
	v_add_f32_dpp v92, v92, v92 quad_perm:[2,3,0,1] row_mask:0xf bank_mask:0xf bound_ctrl:1
	v_add_f32_e32 v98, v90, v91
	ds_read_b128 v[108:111], v128 offset:14144
	v_add_f32_dpp v92, v92, v92 row_half_mirror row_mask:0xf bank_mask:0xf bound_ctrl:1
	ds_read_b128 v[36:39], v105 offset:32256
	v_add_f32_dpp v102, v102, v102 quad_perm:[2,3,0,1] row_mask:0xf bank_mask:0xf bound_ctrl:1
	v_add_f32_dpp v92, v92, v92 row_mirror row_mask:0xf bank_mask:0xf bound_ctrl:1
	v_pk_fma_f32 v[116:117], v[72:73], v[92:93], v[86:87] op_sel_hi:[1,0,1]
	v_pk_fma_f32 v[118:119], v[74:75], v[92:93], v[88:89] op_sel_hi:[1,0,1]
	ds_write_b32 v107, v102 offset:1024
	s_waitcnt lgkmcnt(3)
	v_pk_mul_f32 v[84:85], v[116:117], v[8:9]
	v_pk_mul_f32 v[86:87], v[80:81], v[4:5] op_sel_hi:[0,1]
	v_pk_fma_f32 v[84:85], v[118:119], v[10:11], v[84:85]
	v_pk_mul_f32 v[88:89], v[80:81], v[6:7] op_sel_hi:[0,1]
	v_add_f32_e32 v92, v84, v85
	v_pk_fma_f32 v[86:87], v[116:117], v[16:17], v[86:87]
	v_pk_mul_f32 v[90:91], v[116:117], v[60:61]
	v_add_f32_dpp v92, v92, v92 quad_perm:[1,0,3,2] row_mask:0xf bank_mask:0xf bound_ctrl:1
	v_pk_fma_f32 v[88:89], v[118:119], v[18:19], v[88:89]
	v_pk_fma_f32 v[90:91], v[118:119], v[62:63], v[90:91]
	s_waitcnt lgkmcnt(2)
	v_mfma_f32_32x32x16_bf16 v[40:55], v[108:111], v[124:127], 0
	v_add_f32_dpp v92, v92, v92 quad_perm:[2,3,0,1] row_mask:0xf bank_mask:0xf bound_ctrl:1
	v_add_f32_e32 v99, v90, v91
	ds_read_b128 v[112:115], v128 offset:14688
	v_cndmask_b32_e64 v100, v98, v96, s[38:39]
	v_cndmask_b32_e64 v102, v96, v98, s[38:39]
	v_add_f32_dpp v92, v92, v92 row_half_mirror row_mask:0xf bank_mask:0xf bound_ctrl:1
	ds_read_b128 v[56:59], v105 offset:33536
	v_cndmask_b32_e64 v101, v99, v97, s[38:39]
	v_cndmask_b32_e64 v103, v97, v99, s[38:39]
	v_add_f32_dpp v92, v92, v92 row_mirror row_mask:0xf bank_mask:0xf bound_ctrl:1
	v_pk_fma_f32 v[116:117], v[12:13], v[92:93], v[86:87] op_sel_hi:[1,0,1]
	v_pk_fma_f32 v[118:119], v[14:15], v[92:93], v[88:89] op_sel_hi:[1,0,1]
	s_waitcnt lgkmcnt(3)
	v_pk_mul_f32 v[84:85], v[116:117], v[28:29]
	v_pk_mul_f32 v[86:87], v[80:81], v[24:25] op_sel:[1,0]
	v_pk_fma_f32 v[84:85], v[118:119], v[30:31], v[84:85]
	v_pk_mul_f32 v[88:89], v[80:81], v[26:27] op_sel:[1,0]
	v_add_f32_e32 v92, v84, v85
	v_pk_fma_f32 v[86:87], v[116:117], v[36:37], v[86:87]
	v_pk_mul_f32 v[90:91], v[116:117], v[0:1]
	v_add_f32_dpp v92, v92, v92 quad_perm:[1,0,3,2] row_mask:0xf bank_mask:0xf bound_ctrl:1
	v_pk_fma_f32 v[88:89], v[118:119], v[38:39], v[88:89]
	v_pk_fma_f32 v[90:91], v[118:119], v[2:3], v[90:91]
	s_waitcnt lgkmcnt(1)
	v_mfma_f32_32x32x16_bf16 v[60:75], v[112:115], v[124:127], 0
	v_add_f32_dpp v92, v92, v92 quad_perm:[2,3,0,1] row_mask:0xf bank_mask:0xf bound_ctrl:1
	v_add_f32_e32 v96, v90, v91
	ds_read_b128 v[108:111], v128 offset:15232
	v_add_f32_dpp v102, v102, v100 row_ror:8 row_mask:0xf bank_mask:0xf bound_ctrl:1
	v_add_f32_dpp v92, v92, v92 row_half_mirror row_mask:0xf bank_mask:0xf bound_ctrl:1
	ds_read_b128 v[76:79], v105 offset:34816
	v_add_f32_dpp v103, v103, v101 row_ror:8 row_mask:0xf bank_mask:0xf bound_ctrl:1
	v_add_f32_dpp v92, v92, v92 row_mirror row_mask:0xf bank_mask:0xf bound_ctrl:1
	v_cndmask_b32_e64 v104, v103, v102, s[40:41]
	v_cndmask_b32_e64 v102, v102, v103, s[40:41]
	v_pk_fma_f32 v[116:117], v[32:33], v[92:93], v[86:87] op_sel_hi:[1,0,1]
	v_pk_fma_f32 v[118:119], v[34:35], v[92:93], v[88:89] op_sel_hi:[1,0,1]
	s_waitcnt lgkmcnt(2)
	v_pk_mul_f32 v[84:85], v[116:117], v[48:49]
	v_pk_mul_f32 v[86:87], v[82:83], v[44:45] op_sel_hi:[0,1]
	v_pk_fma_f32 v[84:85], v[118:119], v[50:51], v[84:85]
	v_pk_mul_f32 v[88:89], v[82:83], v[46:47] op_sel_hi:[0,1]
	v_add_f32_e32 v92, v84, v85
	v_pk_fma_f32 v[86:87], v[116:117], v[56:57], v[86:87]
	v_pk_mul_f32 v[90:91], v[116:117], v[20:21]
	v_add_f32_dpp v92, v92, v92 quad_perm:[1,0,3,2] row_mask:0xf bank_mask:0xf bound_ctrl:1
	v_pk_fma_f32 v[88:89], v[118:119], v[58:59], v[88:89]
	v_pk_fma_f32 v[90:91], v[118:119], v[22:23], v[90:91]
	s_waitcnt lgkmcnt(1)
	v_mfma_f32_32x32x16_bf16 v[0:15], v[108:111], v[124:127], 0
	v_add_f32_dpp v92, v92, v92 quad_perm:[2,3,0,1] row_mask:0xf bank_mask:0xf bound_ctrl:1
	v_add_f32_e32 v97, v90, v91
	ds_read_b128 v[112:115], v128 offset:15776
	v_add_f32_dpp v92, v92, v92 row_half_mirror row_mask:0xf bank_mask:0xf bound_ctrl:1
	ds_read_b128 v[16:19], v105 offset:36096
	v_add_f32_dpp v102, v102, v104 row_half_mirror row_mask:0xf bank_mask:0xf bound_ctrl:1
	v_add_f32_dpp v92, v92, v92 row_mirror row_mask:0xf bank_mask:0xf bound_ctrl:1
	v_pk_fma_f32 v[116:117], v[52:53], v[92:93], v[86:87] op_sel_hi:[1,0,1]
	v_pk_fma_f32 v[118:119], v[54:55], v[92:93], v[88:89] op_sel_hi:[1,0,1]
	v_add_f32_dpp v102, v102, v102 quad_perm:[1,0,3,2] row_mask:0xf bank_mask:0xf bound_ctrl:1
	s_waitcnt lgkmcnt(2)
	v_pk_mul_f32 v[84:85], v[116:117], v[68:69]
	v_pk_mul_f32 v[86:87], v[82:83], v[64:65] op_sel:[1,0]
	v_pk_fma_f32 v[84:85], v[118:119], v[70:71], v[84:85]
	v_pk_mul_f32 v[88:89], v[82:83], v[66:67] op_sel:[1,0]
	ds_read_b128 v[80:83], v106 offset:112
	v_add_f32_e32 v92, v84, v85
	v_pk_fma_f32 v[86:87], v[116:117], v[76:77], v[86:87]
	v_pk_mul_f32 v[90:91], v[116:117], v[40:41]
	v_add_f32_dpp v92, v92, v92 quad_perm:[1,0,3,2] row_mask:0xf bank_mask:0xf bound_ctrl:1
	v_pk_fma_f32 v[88:89], v[118:119], v[78:79], v[88:89]
	v_pk_fma_f32 v[90:91], v[118:119], v[42:43], v[90:91]
	s_waitcnt lgkmcnt(2)
; #define YRED4(dst) { \
;           float a0 = b3 ? p2 : p0, a1 = b3 ? p3 : p1; const float s0 = b3 ? p0 : p2, s1 = b3 ? p1 : p3; \
;           a0 += dppf<0x128>(s0); a1 += dppf<0x128>(s1); \
;           float cc = b2 ? a1 : a0; const float dd = b2 ? a0 : a1; \
;           cc += dppf<0x141>(dd); cc += dppf<0xB1>(cc); cc += dppf<0x4E>(cc); dst = cc; }
; __device__ __forceinline__ void phase_scan(KP p) {
;     ...
;         SLD(A, 0); SLD(B, 1);
;         for (int g = 0; g < 8; ++g) {
;           const int st = g * 4;
;           SLD(C, st + 2); vnext = *(const float4*)(vb4 + st + 4);
;           __builtin_amdgcn_sched_barrier(0);
;           if (g > 0) { float yv; YRED4(yv); yb[(st - 4) * 16] = yv; }
;           SCOMP(A, vcur.x, q0);
;           SLD(D, st + 3);
;           __builtin_amdgcn_sched_barrier(0);
;           SCOMP(B, vcur.y, q1);
;           SLD(A, st + 4);
;           __builtin_amdgcn_sched_barrier(0);
;           SCOMP(C, vcur.z, q2);
;           SLD(B, st + 5);
;           __builtin_amdgcn_sched_barrier(0);
;           SCOMP(D, vcur.w, q3);
;           vcur = vnext; p0 = q0; p1 = q1; p2 = q2; p3 = q3;
;         }
;         { float yv; YRED4(yv); yb[28 * 16] = yv; }
	v_mfma_f32_32x32x16_bf16 v[20:35], v[112:115], v[124:127], 0
	v_add_f32_dpp v92, v92, v92 quad_perm:[2,3,0,1] row_mask:0xf bank_mask:0xf bound_ctrl:1
	v_add_f32_e32 v98, v90, v91
	ds_read_b128 v[108:111], v128 offset:16320
	v_add_f32_dpp v92, v92, v92 row_half_mirror row_mask:0xf bank_mask:0xf bound_ctrl:1
	ds_read_b128 v[36:39], v105 offset:37376
	v_add_f32_dpp v102, v102, v102 quad_perm:[2,3,0,1] row_mask:0xf bank_mask:0xf bound_ctrl:1
	v_add_f32_dpp v92, v92, v92 row_mirror row_mask:0xf bank_mask:0xf bound_ctrl:1
	v_pk_fma_f32 v[116:117], v[72:73], v[92:93], v[86:87] op_sel_hi:[1,0,1]
	v_pk_fma_f32 v[118:119], v[74:75], v[92:93], v[88:89] op_sel_hi:[1,0,1]
	ds_write_b32 v107, v102 offset:1280
	s_waitcnt lgkmcnt(3)
	v_pk_mul_f32 v[84:85], v[116:117], v[8:9]
	v_pk_mul_f32 v[86:87], v[80:81], v[4:5] op_sel_hi:[0,1]
	v_pk_fma_f32 v[84:85], v[118:119], v[10:11], v[84:85]
	v_pk_mul_f32 v[88:89], v[80:81], v[6:7] op_sel_hi:[0,1]
	v_add_f32_e32 v92, v84, v85
	v_pk_fma_f32 v[86:87], v[116:117], v[16:17], v[86:87]
	v_pk_mul_f32 v[90:91], v[116:117], v[60:61]
	v_add_f32_dpp v92, v92, v92 quad_perm:[1,0,3,2] row_mask:0xf bank_mask:0xf bound_ctrl:1
	v_pk_fma_f32 v[88:89], v[118:119], v[18:19], v[88:89]
	v_pk_fma_f32 v[90:91], v[118:119], v[62:63], v[90:91]
	s_waitcnt lgkmcnt(2)
	v_mfma_f32_32x32x16_bf16 v[40:55], v[108:111], v[124:127], 0
	v_add_f32_dpp v92, v92, v92 quad_perm:[2,3,0,1] row_mask:0xf bank_mask:0xf bound_ctrl:1
	v_add_f32_e32 v99, v90, v91
	ds_read_b128 v[112:115], v128 offset:16864
	v_cndmask_b32_e64 v100, v98, v96, s[38:39]
	v_cndmask_b32_e64 v102, v96, v98, s[38:39]
	v_add_f32_dpp v92, v92, v92 row_half_mirror row_mask:0xf bank_mask:0xf bound_ctrl:1
	ds_read_b128 v[56:59], v105 offset:38656
	v_cndmask_b32_e64 v101, v99, v97, s[38:39]
	v_cndmask_b32_e64 v103, v97, v99, s[38:39]
	v_add_f32_dpp v92, v92, v92 row_mirror row_mask:0xf bank_mask:0xf bound_ctrl:1
	v_pk_fma_f32 v[116:117], v[12:13], v[92:93], v[86:87] op_sel_hi:[1,0,1]
	v_pk_fma_f32 v[118:119], v[14:15], v[92:93], v[88:89] op_sel_hi:[1,0,1]
	s_waitcnt lgkmcnt(3)
	v_pk_mul_f32 v[84:85], v[116:117], v[28:29]
	v_pk_mul_f32 v[86:87], v[80:81], v[24:25] op_sel:[1,0]
	v_pk_fma_f32 v[84:85], v[118:119], v[30:31], v[84:85]
	v_pk_mul_f32 v[88:89], v[80:81], v[26:27] op_sel:[1,0]
	v_add_f32_e32 v92, v84, v85
	v_pk_fma_f32 v[86:87], v[116:117], v[36:37], v[86:87]
	v_pk_mul_f32 v[90:91], v[116:117], v[0:1]
	v_add_f32_dpp v92, v92, v92 quad_perm:[1,0,3,2] row_mask:0xf bank_mask:0xf bound_ctrl:1
	v_pk_fma_f32 v[88:89], v[118:119], v[38:39], v[88:89]
	v_pk_fma_f32 v[90:91], v[118:119], v[2:3], v[90:91]
	s_waitcnt lgkmcnt(1)
	v_mfma_f32_32x32x16_bf16 v[60:75], v[112:115], v[124:127], 0
	v_add_f32_dpp v92, v92, v92 quad_perm:[2,3,0,1] row_mask:0xf bank_mask:0xf bound_ctrl:1
	v_add_f32_e32 v96, v90, v91
	v_add_f32_dpp v102, v102, v100 row_ror:8 row_mask:0xf bank_mask:0xf bound_ctrl:1
	v_add_f32_dpp v92, v92, v92 row_half_mirror row_mask:0xf bank_mask:0xf bound_ctrl:1
	ds_read_b128 v[76:79], v105 offset:39936
	v_add_f32_dpp v103, v103, v101 row_ror:8 row_mask:0xf bank_mask:0xf bound_ctrl:1
	v_add_f32_dpp v92, v92, v92 row_mirror row_mask:0xf bank_mask:0xf bound_ctrl:1
	v_cndmask_b32_e64 v104, v103, v102, s[40:41]
	v_cndmask_b32_e64 v102, v102, v103, s[40:41]
	v_pk_fma_f32 v[116:117], v[32:33], v[92:93], v[86:87] op_sel_hi:[1,0,1]
	v_pk_fma_f32 v[118:119], v[34:35], v[92:93], v[88:89] op_sel_hi:[1,0,1]
	s_waitcnt lgkmcnt(1)
	v_pk_mul_f32 v[84:85], v[116:117], v[48:49]
	v_pk_mul_f32 v[86:87], v[82:83], v[44:45] op_sel_hi:[0,1]
	v_pk_fma_f32 v[84:85], v[118:119], v[50:51], v[84:85]
	v_pk_mul_f32 v[88:89], v[82:83], v[46:47] op_sel_hi:[0,1]
	v_add_f32_e32 v92, v84, v85
	v_pk_fma_f32 v[86:87], v[116:117], v[56:57], v[86:87]
	v_pk_mul_f32 v[90:91], v[116:117], v[20:21]
	v_add_f32_dpp v92, v92, v92 quad_perm:[1,0,3,2] row_mask:0xf bank_mask:0xf bound_ctrl:1
	v_pk_fma_f32 v[88:89], v[118:119], v[58:59], v[88:89]
	v_pk_fma_f32 v[90:91], v[118:119], v[22:23], v[90:91]
	v_add_f32_dpp v92, v92, v92 quad_perm:[2,3,0,1] row_mask:0xf bank_mask:0xf bound_ctrl:1
	v_add_f32_e32 v97, v90, v91
	s_nop 0
	v_add_f32_dpp v92, v92, v92 row_half_mirror row_mask:0xf bank_mask:0xf bound_ctrl:1
	v_add_f32_dpp v102, v102, v104 row_half_mirror row_mask:0xf bank_mask:0xf bound_ctrl:1
	s_nop 0
	v_add_f32_dpp v92, v92, v92 row_mirror row_mask:0xf bank_mask:0xf bound_ctrl:1
	v_pk_fma_f32 v[116:117], v[52:53], v[92:93], v[86:87] op_sel_hi:[1,0,1]
	v_pk_fma_f32 v[118:119], v[54:55], v[92:93], v[88:89] op_sel_hi:[1,0,1]
	v_add_f32_dpp v102, v102, v102 quad_perm:[1,0,3,2] row_mask:0xf bank_mask:0xf bound_ctrl:1
	s_waitcnt lgkmcnt(0)
	v_pk_mul_f32 v[84:85], v[116:117], v[68:69]
	v_pk_mul_f32 v[86:87], v[82:83], v[64:65] op_sel:[1,0]
	v_pk_fma_f32 v[84:85], v[118:119], v[70:71], v[84:85]
	v_pk_mul_f32 v[88:89], v[82:83], v[66:67] op_sel:[1,0]
	v_add_f32_e32 v92, v84, v85
	v_pk_fma_f32 v[86:87], v[116:117], v[76:77], v[86:87]
	v_pk_mul_f32 v[90:91], v[116:117], v[40:41]
	v_add_f32_dpp v92, v92, v92 quad_perm:[1,0,3,2] row_mask:0xf bank_mask:0xf bound_ctrl:1
	v_pk_fma_f32 v[88:89], v[118:119], v[78:79], v[88:89]
	v_pk_fma_f32 v[90:91], v[118:119], v[42:43], v[90:91]
	v_add_f32_dpp v92, v92, v92 quad_perm:[2,3,0,1] row_mask:0xf bank_mask:0xf bound_ctrl:1
	v_add_f32_e32 v98, v90, v91
	s_nop 0
	v_add_f32_dpp v92, v92, v92 row_half_mirror row_mask:0xf bank_mask:0xf bound_ctrl:1
	v_add_f32_dpp v102, v102, v102 quad_perm:[2,3,0,1] row_mask:0xf bank_mask:0xf bound_ctrl:1
	s_nop 0
	v_add_f32_dpp v92, v92, v92 row_mirror row_mask:0xf bank_mask:0xf bound_ctrl:1
	v_pk_fma_f32 v[116:117], v[72:73], v[92:93], v[86:87] op_sel_hi:[1,0,1]
	v_pk_fma_f32 v[118:119], v[74:75], v[92:93], v[88:89] op_sel_hi:[1,0,1]
	ds_write_b32 v107, v102 offset:1536
	v_cndmask_b32_e64 v100, v98, v96, s[38:39]
	v_pk_mul_f32 v[90:91], v[116:117], v[60:61]
	v_cndmask_b32_e64 v102, v96, v98, s[38:39]
	v_pk_fma_f32 v[90:91], v[118:119], v[62:63], v[90:91]
	s_nop 0
	v_add_f32_e32 v99, v90, v91
	v_add_f32_dpp v102, v102, v100 row_ror:8 row_mask:0xf bank_mask:0xf bound_ctrl:1
	v_cndmask_b32_e64 v101, v99, v97, s[38:39]
	v_cndmask_b32_e64 v103, v97, v99, s[38:39]
	s_nop 1
	v_add_f32_dpp v103, v103, v101 row_ror:8 row_mask:0xf bank_mask:0xf bound_ctrl:1
	v_cndmask_b32_e64 v104, v103, v102, s[40:41]
	v_cndmask_b32_e64 v102, v102, v103, s[40:41]
	s_nop 1
	v_add_f32_dpp v102, v102, v104 row_half_mirror row_mask:0xf bank_mask:0xf bound_ctrl:1
	s_nop 1
	v_add_f32_dpp v102, v102, v102 quad_perm:[1,0,3,2] row_mask:0xf bank_mask:0xf bound_ctrl:1
	s_nop 1
	v_add_f32_dpp v102, v102, v102 quad_perm:[2,3,0,1] row_mask:0xf bank_mask:0xf bound_ctrl:1
	ds_write_b32 v107, v102 offset:1792
	s_branch .LBB0_755
